# layer-1 input projection tile order: V column tiles in the first round, three-tile workgroups get only q, k and za tiles (cheapest epilogues)
# baseline (speedup 1.0000x reference)
.LBB0_44:
	s_lshl_b32 s8, s14, 3
	v_cvt_f32_u32_e32 v0, s8
	s_sub_i32 s9, 0, s8
	s_ashr_i32 s7, s7, 3
	s_add_i32 s7, s10, s7
	v_rcp_iflag_f32_e32 v0, v0
	s_abs_i32 s11, s7
	s_ashr_i32 s10, s7, 31
	v_mul_f32_e32 v0, 0x4f7ffffe, v0
	v_cvt_u32_f32_e32 v0, v0
	s_nop 0
	v_readfirstlane_b32 s12, v0
	s_mul_i32 s9, s9, s12
	s_mul_hi_u32 s9, s12, s9
	s_add_i32 s12, s12, s9
	s_mul_hi_u32 s9, s11, s12
	s_mul_i32 s12, s9, s8
	s_sub_i32 s11, s11, s12
	s_add_i32 s13, s9, 1
	s_sub_i32 s12, s11, s8
	s_cmp_ge_u32 s11, s8
	s_cselect_b32 s9, s13, s9
	s_cselect_b32 s11, s12, s11
	s_add_i32 s12, s9, 1
	s_cmp_ge_u32 s11, s8
	s_cselect_b32 s9, s12, s9
	s_xor_b32 s9, s9, s10
	s_sub_i32 s9, s9, s10
	s_lshl_b32 s10, s9, 3
	s_mul_i32 s9, s9, s8
	v_readlane_b32 s8, v253, 61
	s_sub_i32 s8, s8, s10
	s_min_i32 s11, s8, 8
	s_sext_i32_i16 s8, s11
	v_cvt_f32_i32_e32 v0, s8
	s_sub_i32 s7, s7, s9
	s_sext_i32_i16 s9, s7
	v_cvt_f32_i32_e32 v2, s9
	v_rcp_iflag_f32_e32 v3, v0
	s_xor_b32 s8, s9, s8
	s_ashr_i32 s8, s8, 30
	s_or_b32 s12, s8, 1
	v_mul_f32_e32 v3, v2, v3
	v_trunc_f32_e32 v3, v3
	v_fma_f32 v2, -v3, v0, v2
	v_cvt_i32_f32_e32 v3, v3
	v_cmp_ge_f32_e64 s[8:9], |v2|, |v0|
	s_and_b64 s[8:9], s[8:9], exec
	s_cselect_b32 s8, s12, 0
	v_readfirstlane_b32 s9, v3
	s_add_i32 s8, s9, s8
	s_mul_i32 s11, s8, s11
	s_sub_i32 s7, s7, s11
	s_sext_i32_i16 s9, s8
	s_sext_i32_i16 s7, s7
	s_add_i32 s34, s10, s7
	s_add_i32 s7, s9, 1
	s_and_b32 s8, s8, 0xffff
	s_cmp_lg_u32 s8, 8
	s_cselect_b32 s7, s7, 0
	v_readlane_b32 s8, v253, 55
	s_cmp_eq_u32 s8, 1
	s_cbranch_scc0 .Lpn0_keep
	s_mov_b32 s8, s7
	s_cmp_eq_u32 s8, 3
	s_cselect_b32 s7, 5, s7
	s_cmp_eq_u32 s8, 4
	s_cselect_b32 s7, 6, s7

.LBB0_60:
	s_ashr_i32 s0, s8, 3
	s_add_i32 s0, s14, s0
	s_abs_i32 s8, s0
	v_readlane_b32 s9, v254, 45
	s_mul_hi_u32 s9, s8, s9
	s_mul_i32 s14, s9, s69
	s_sub_i32 s8, s8, s14
	s_ashr_i32 s1, s0, 31
	s_add_i32 s14, s9, 1
	s_sub_i32 s15, s8, s69
	s_cmp_ge_u32 s8, s69
	s_cselect_b32 s9, s14, s9
	s_cselect_b32 s8, s15, s8
	s_add_i32 s14, s9, 1
	s_cmp_ge_u32 s8, s69
	s_cselect_b32 s8, s14, s9
	s_xor_b32 s8, s8, s1
	s_sub_i32 s1, s8, s1
	s_lshl_b32 s8, s1, 3
	v_readlane_b32 s9, v253, 61
	s_sub_i32 s9, s9, s8
	s_min_i32 s9, s9, 8
	s_abs_i32 s14, s9
	v_cvt_f32_u32_e32 v0, s14
	s_sub_i32 s17, 0, s14
	s_mul_i32 s1, s1, s69
	s_sub_i32 s0, s0, s1
	v_rcp_iflag_f32_e32 v0, v0
	s_abs_i32 s1, s0
	s_xor_b32 s15, s0, s9
	s_ashr_i32 s15, s15, 31
	v_mul_f32_e32 v0, 0x4f7ffffe, v0
	v_cvt_u32_f32_e32 v0, v0
	s_nop 0
	v_readfirstlane_b32 s18, v0
	s_mul_i32 s17, s17, s18
	s_mul_hi_u32 s17, s18, s17
	s_add_i32 s18, s18, s17
	s_mul_hi_u32 s17, s1, s18
	s_mul_i32 s18, s17, s14
	s_sub_i32 s1, s1, s18
	s_add_i32 s18, s17, 1
	s_sub_i32 s22, s1, s14
	s_cmp_ge_u32 s1, s14
	s_cselect_b32 s17, s18, s17
	s_cselect_b32 s1, s22, s1
	s_add_i32 s18, s17, 1
	s_cmp_ge_u32 s1, s14
	s_cselect_b32 s1, s18, s17
	s_xor_b32 s1, s1, s15
	s_sub_i32 s14, s1, s15
	s_mul_i32 s1, s14, s9
	s_sub_i32 s0, s0, s1
	s_add_i32 s97, s0, s8
	s_add_i32 s0, s14, 1
	s_cmp_lg_u32 s14, 8
	s_cselect_b32 s8, s0, 0
	v_readlane_b32 s0, v253, 55
	s_cmp_eq_u32 s0, 1
	s_cbranch_scc0 .Lpn_keep
	s_mov_b32 s0, s8
	s_cmp_eq_u32 s0, 5
	s_cselect_b32 s8, 3, s8
	s_cmp_eq_u32 s0, 6
	s_cselect_b32 s8, 4, s8
